# P1 keeps four rows in flight per wave (loop body duplicated with renamed registers) on top of the reversed final pass
# speedup vs baseline: 1.0058x; 1.0034x over previous
; __device__ __forceinline__ u32x4 pk8(f32x4 a, f32x4 b) { u32x4 w; w.x = pk2(a[0], a[1]); w.y = pk2(a[2], a[3]); w.z = pk2(b[0], b[1]); w.w = pk2(b[2], b[3]); return w; }
; __device__ __forceinline__ float sumsq4(f32x4 x) { return (x[0] * x[0] + x[1] * x[1]) + (x[2] * x[2] + x[3] * x[3]); }
; __device__ __forceinline__ void phase1(const Ptrs& P, int G) {
;     ...
;     for (int row0 = gw; row0 < T; row0 += 2 * NGW) {
;         f32x4 v[2][2][2];
; #pragma unroll
;         for (int r = 0; r < 2; ++r) { const int row = row0 + r * NGW; if (row < T) { const float* xr = P.x + (size_t)row * DM + 8 * lane;
; #pragma unroll
;             for (int j = 0; j < 2; ++j) { v[r][j][0] = __builtin_nontemporal_load((const f32x4*)(xr + 512 * j)); v[r][j][1] = __builtin_nontemporal_load((const f32x4*)(xr + 512 * j + 4)); } } }
; #pragma unroll
;         for (int r = 0; r < 2; ++r) { const int row = row0 + r * NGW; if (row < T) {
;             float s = 0.f;
; #pragma unroll
;             for (int j = 0; j < 2; ++j) s += sumsq4(v[r][j][0]) + sumsq4(v[r][j][1]);
;             const int b = row >> 11;
;             const float rstd = __builtin_amdgcn_rsqf(wave_sum(s) * (1.0f / DM) + EPS);
; #pragma unroll
;             for (int j = 0; j < 2; ++j) {
;                 const int col = 512 * j + 8 * lane;
;                 const f32x4 sha = *(const f32x4*)(mod + b * 3072 + col), shb = *(const f32x4*)(mod + b * 3072 + col + 4);
;                 const f32x4 sca = *(const f32x4*)(mod + b * 3072 + 1024 + col), scb = *(const f32x4*)(mod + b * 3072 + 1024 + col + 4);
;                 const f32x4 ha = v[r][j][0] * rstd * g[j][0] * (sca + 1.0f) + sha, hb = v[r][j][1] * rstd * g[j][1] * (scb + 1.0f) + shb;
;                 *(u32x4*)(H + (size_t)row * DM + col) = pk8(ha, hb);
;             } } }
;     }
.LBB0_282:
	s_or_b64 exec, exec, s[10:11]
	v_add_u32_e32 v96, s13, v56
	v_ashrrev_i32_e32 v97, 31, v96
	v_lshlrev_b64 v[98:99], 12, v[96:97]
	v_lshl_add_u64 v[98:99], v[50:51], 0, v[98:99]
	global_load_dwordx4 v[152:155], v[98:99], off offset:16 nt
	global_load_dwordx4 v[156:159], v[98:99], off nt
	global_load_dwordx4 v[144:147], v[98:99], off offset:2064 nt
	global_load_dwordx4 v[148:151], v[98:99], off offset:2048 nt
	v_add_u32_e32 v100, s13, v96
	v_ashrrev_i32_e32 v101, 31, v100
	v_lshlrev_b64 v[98:99], 12, v[100:101]
	v_lshl_add_u64 v[98:99], v[50:51], 0, v[98:99]
	global_load_dwordx4 v[128:131], v[98:99], off offset:16 nt
	global_load_dwordx4 v[132:135], v[98:99], off nt
	global_load_dwordx4 v[136:139], v[98:99], off offset:2064 nt
	global_load_dwordx4 v[140:143], v[98:99], off offset:2048 nt
	v_ashrrev_i32_e32 v55, 11, v58
	v_mul_i32_i24_e32 v68, 0xc00, v55
	v_ashrrev_i32_e32 v69, 31, v68
	v_lshl_add_u64 v[76:77], v[68:69], 2, s[4:5]
	v_lshl_add_u64 v[86:87], v[76:77], 0, s[8:9]
	v_lshl_add_u64 v[78:79], v[86:87], 0, v[48:49]
	global_load_dwordx4 v[68:71], v[78:79], off offset:16
	global_load_dwordx4 v[72:75], v[78:79], off
	v_lshl_add_u64 v[88:89], v[76:77], 0, v[48:49]
	global_load_dwordx4 v[76:79], v[88:89], off offset:16
	global_load_dwordx4 v[80:83], v[88:89], off
	s_waitcnt vmcnt(6)
	v_mov_b32_e32 v90, v45
	s_waitcnt vmcnt(4)
	v_mov_b32_e32 v91, v37
	v_mov_b32_e32 v84, v44
	v_mov_b32_e32 v85, v36
	v_pk_mul_f32 v[90:91], v[90:91], v[90:91]
	v_mov_b32_e32 v92, v47
	v_mov_b32_e32 v93, v39
	v_pk_fma_f32 v[84:85], v[84:85], v[84:85], v[90:91]
	v_mov_b32_e32 v90, v46
	v_mov_b32_e32 v91, v38
	v_pk_mul_f32 v[92:93], v[92:93], v[92:93]
	v_mov_b32_e32 v94, v43
	v_pk_fma_f32 v[90:91], v[90:91], v[90:91], v[92:93]
	v_mov_b32_e32 v92, v41
	v_mov_b32_e32 v93, v33
	v_pk_add_f32 v[84:85], v[84:85], v[90:91]
	v_mov_b32_e32 v90, v40
	v_mov_b32_e32 v91, v32
	v_pk_mul_f32 v[92:93], v[92:93], v[92:93]
	v_mov_b32_e32 v95, v35
	v_pk_fma_f32 v[90:91], v[90:91], v[90:91], v[92:93]
	v_mov_b32_e32 v92, v42
	v_mov_b32_e32 v93, v34
	v_pk_mul_f32 v[94:95], v[94:95], v[94:95]
	v_lshlrev_b64 v[58:59], 11, v[58:59]
	v_pk_fma_f32 v[92:93], v[92:93], v[92:93], v[94:95]
	v_lshl_add_u64 v[58:59], v[52:53], 0, v[58:59]
	v_pk_add_f32 v[90:91], v[90:91], v[92:93]
	s_waitcnt vmcnt(3)
	v_pk_add_f32 v[70:71], v[70:71], 1.0 op_sel_hi:[1,0]
	v_pk_add_f32 v[84:85], v[84:85], v[90:91]
	s_waitcnt vmcnt(2)
	v_pk_add_f32 v[74:75], v[74:75], 1.0 op_sel_hi:[1,0]
	v_add_f32_e32 v55, v84, v85
	ds_bpermute_b32 v67, v60, v55
	v_pk_add_f32 v[72:73], v[72:73], 1.0 op_sel_hi:[1,0]
	v_pk_add_f32 v[68:69], v[68:69], 1.0 op_sel_hi:[1,0]
	s_waitcnt lgkmcnt(0)
	v_add_f32_e32 v55, v55, v67
	ds_bpermute_b32 v67, v61, v55
	s_waitcnt lgkmcnt(0)
	v_add_f32_e32 v55, v55, v67
	ds_bpermute_b32 v67, v62, v55
	s_waitcnt lgkmcnt(0)
	v_add_f32_e32 v55, v55, v67
	ds_bpermute_b32 v67, v63, v55
	s_waitcnt lgkmcnt(0)
	v_add_f32_e32 v55, v55, v67
	ds_bpermute_b32 v67, v64, v55
	s_waitcnt lgkmcnt(0)
	v_add_f32_e32 v55, v55, v67
	ds_bpermute_b32 v67, v65, v55
	s_waitcnt lgkmcnt(0)
	v_add_f32_e32 v55, v55, v67
	v_fmamk_f32 v55, v55, 0x3a800000, v66
	v_rsq_f32_e32 v84, v55
	v_mov_b32_e32 v55, v49
	v_lshl_add_u64 v[86:87], v[86:87], 0, v[54:55]
	v_pk_mul_f32 v[46:47], v[46:47], v[84:85] op_sel_hi:[1,0]
	v_pk_mul_f32 v[44:45], v[44:45], v[84:85] op_sel_hi:[1,0]
	v_pk_mul_f32 v[42:43], v[42:43], v[84:85] op_sel_hi:[1,0]
	v_pk_mul_f32 v[40:41], v[40:41], v[84:85] op_sel_hi:[1,0]
	v_pk_mul_f32 v[44:45], v[4:5], v[44:45]
	v_pk_mul_f32 v[46:47], v[6:7], v[46:47]
	v_pk_mul_f32 v[40:41], v[0:1], v[40:41]
	v_pk_mul_f32 v[42:43], v[2:3], v[42:43]
	s_waitcnt vmcnt(0)
	v_pk_fma_f32 v[46:47], v[74:75], v[46:47], v[82:83]
	v_pk_fma_f32 v[44:45], v[72:73], v[44:45], v[80:81]
	v_pk_fma_f32 v[70:71], v[70:71], v[42:43], v[78:79]
	v_pk_fma_f32 v[42:43], v[68:69], v[40:41], v[76:77]
	v_cvt_pk_bf16_f32 v40, v44, v45
	v_cvt_pk_bf16_f32 v41, v46, v47
	v_cvt_pk_bf16_f32 v42, v42, v43
	v_cvt_pk_bf16_f32 v43, v70, v71
	global_store_dwordx4 v[58:59], v[40:43], off
	global_load_dwordx4 v[40:43], v[86:87], off
	s_nop 0
	global_load_dwordx4 v[44:47], v[86:87], off offset:16
	global_load_dwordx4 v[68:71], v[88:89], off offset:2048
	global_load_dwordx4 v[72:75], v[88:89], off offset:2064
	v_pk_mul_f32 v[38:39], v[38:39], v[84:85] op_sel_hi:[1,0]
	v_pk_mul_f32 v[36:37], v[36:37], v[84:85] op_sel_hi:[1,0]
	v_pk_mul_f32 v[34:35], v[34:35], v[84:85] op_sel_hi:[1,0]
	v_pk_mul_f32 v[32:33], v[32:33], v[84:85] op_sel_hi:[1,0]
	v_pk_mul_f32 v[36:37], v[12:13], v[36:37]
	v_pk_mul_f32 v[38:39], v[14:15], v[38:39]
	v_pk_mul_f32 v[32:33], v[8:9], v[32:33]
	v_pk_mul_f32 v[34:35], v[10:11], v[34:35]
	s_waitcnt vmcnt(3)
	v_pk_add_f32 v[42:43], v[42:43], 1.0 op_sel_hi:[1,0]
	v_pk_add_f32 v[40:41], v[40:41], 1.0 op_sel_hi:[1,0]
	s_waitcnt vmcnt(2)
	v_pk_add_f32 v[46:47], v[46:47], 1.0 op_sel_hi:[1,0]
	v_pk_add_f32 v[44:45], v[44:45], 1.0 op_sel_hi:[1,0]
	s_waitcnt vmcnt(1)
	v_pk_fma_f32 v[38:39], v[42:43], v[38:39], v[70:71]
	v_pk_fma_f32 v[36:37], v[40:41], v[36:37], v[68:69]
	s_waitcnt vmcnt(0)
	v_pk_fma_f32 v[40:41], v[34:35], v[46:47], v[74:75]
	v_pk_fma_f32 v[34:35], v[32:33], v[44:45], v[72:73]
	v_cvt_pk_bf16_f32 v32, v36, v37
	v_cvt_pk_bf16_f32 v33, v38, v39
	v_cvt_pk_bf16_f32 v34, v34, v35
	v_cvt_pk_bf16_f32 v35, v40, v41
	global_store_dwordx4 v[58:59], v[32:35], off offset:1024
	s_and_saveexec_b64 s[10:11], vcc
	s_cbranch_execz .Lp1_mid
; __device__ __forceinline__ u32x4 pk8(f32x4 a, f32x4 b) { u32x4 w; w.x = pk2(a[0], a[1]); w.y = pk2(a[2], a[3]); w.z = pk2(b[0], b[1]); w.w = pk2(b[2], b[3]); return w; }
; __device__ __forceinline__ float sumsq4(f32x4 x) { return (x[0] * x[0] + x[1] * x[1]) + (x[2] * x[2] + x[3] * x[3]); }
; __device__ __forceinline__ void phase1(const Ptrs& P, int G) {
;     ...
;         for (int r = 0; r < 2; ++r) { const int row = row0 + r * NGW; if (row < T) {
;             float s = 0.f;
; #pragma unroll
;             for (int j = 0; j < 2; ++j) s += sumsq4(v[r][j][0]) + sumsq4(v[r][j][1]);
;             const int b = row >> 11;
;             const float rstd = __builtin_amdgcn_rsqf(wave_sum(s) * (1.0f / DM) + EPS);
; #pragma unroll
;             for (int j = 0; j < 2; ++j) {
;                 const int col = 512 * j + 8 * lane;
;                 const f32x4 sha = *(const f32x4*)(mod + b * 3072 + col), shb = *(const f32x4*)(mod + b * 3072 + col + 4);
;                 const f32x4 sca = *(const f32x4*)(mod + b * 3072 + 1024 + col), scb = *(const f32x4*)(mod + b * 3072 + 1024 + col + 4);
;                 const f32x4 ha = v[r][j][0] * rstd * g[j][0] * (sca + 1.0f) + sha, hb = v[r][j][1] * rstd * g[j][1] * (scb + 1.0f) + shb;
;                 *(u32x4*)(H + (size_t)row * DM + col) = pk8(ha, hb);
;             } } }
	v_ashrrev_i32_e32 v32, 11, v56
	v_mul_i32_i24_e32 v32, 0xc00, v32
	v_ashrrev_i32_e32 v33, 31, v32
	v_lshl_add_u64 v[40:41], v[32:33], 2, s[4:5]
	v_lshl_add_u64 v[68:69], v[40:41], 0, s[8:9]
	v_lshl_add_u64 v[42:43], v[68:69], 0, v[48:49]
	global_load_dwordx4 v[32:35], v[42:43], off offset:16
	global_load_dwordx4 v[36:39], v[42:43], off
	v_lshl_add_u64 v[70:71], v[40:41], 0, v[48:49]
	global_load_dwordx4 v[40:43], v[70:71], off offset:16
	global_load_dwordx4 v[44:47], v[70:71], off
	v_mov_b32_e32 v72, v29
	v_mov_b32_e32 v73, v21
	v_mov_b32_e32 v58, v28
	v_mov_b32_e32 v59, v20
	v_pk_mul_f32 v[72:73], v[72:73], v[72:73]
	v_mov_b32_e32 v74, v31
	v_mov_b32_e32 v75, v23
	v_pk_fma_f32 v[58:59], v[58:59], v[58:59], v[72:73]
	v_mov_b32_e32 v72, v30
	v_mov_b32_e32 v73, v22
	v_pk_mul_f32 v[74:75], v[74:75], v[74:75]
	v_mov_b32_e32 v76, v27
	v_pk_fma_f32 v[72:73], v[72:73], v[72:73], v[74:75]
	v_mov_b32_e32 v74, v25
	v_mov_b32_e32 v75, v17
	v_pk_add_f32 v[58:59], v[58:59], v[72:73]
	v_mov_b32_e32 v72, v24
	v_mov_b32_e32 v73, v16
	v_pk_mul_f32 v[74:75], v[74:75], v[74:75]
	v_mov_b32_e32 v77, v19
	v_pk_fma_f32 v[72:73], v[72:73], v[72:73], v[74:75]
	v_mov_b32_e32 v74, v26
	v_mov_b32_e32 v75, v18
	v_pk_mul_f32 v[76:77], v[76:77], v[76:77]
	v_lshl_add_u64 v[68:69], v[68:69], 0, v[54:55]
	v_pk_fma_f32 v[74:75], v[74:75], v[74:75], v[76:77]
	s_waitcnt vmcnt(3)
	v_pk_add_f32 v[34:35], v[34:35], 1.0 op_sel_hi:[1,0]
	v_pk_add_f32 v[72:73], v[72:73], v[74:75]
	s_waitcnt vmcnt(2)
	v_pk_add_f32 v[38:39], v[38:39], 1.0 op_sel_hi:[1,0]
	v_pk_add_f32 v[58:59], v[72:73], v[58:59]
	v_pk_add_f32 v[36:37], v[36:37], 1.0 op_sel_hi:[1,0]
	v_add_f32_e32 v58, v58, v59
	ds_bpermute_b32 v59, v60, v58
	v_pk_add_f32 v[32:33], v[32:33], 1.0 op_sel_hi:[1,0]
	v_lshlrev_b64 v[72:73], 11, v[56:57]
	v_lshl_add_u64 v[72:73], v[52:53], 0, v[72:73]
	s_waitcnt lgkmcnt(0)
	v_add_f32_e32 v58, v58, v59
	ds_bpermute_b32 v59, v61, v58
	s_waitcnt lgkmcnt(0)
	v_add_f32_e32 v58, v58, v59
	ds_bpermute_b32 v59, v62, v58
	s_waitcnt lgkmcnt(0)
	v_add_f32_e32 v58, v58, v59
	ds_bpermute_b32 v59, v63, v58
	s_waitcnt lgkmcnt(0)
	v_add_f32_e32 v58, v58, v59
	ds_bpermute_b32 v59, v64, v58
	s_waitcnt lgkmcnt(0)
	v_add_f32_e32 v58, v58, v59
	ds_bpermute_b32 v59, v65, v58
	s_waitcnt lgkmcnt(0)
	v_add_f32_e32 v58, v58, v59
	v_fmamk_f32 v58, v58, 0x3a800000, v66
	v_rsq_f32_e32 v58, v58
	s_nop 0
	v_pk_mul_f32 v[74:75], v[22:23], v[58:59] op_sel_hi:[1,0]
	v_pk_mul_f32 v[76:77], v[20:21], v[58:59] op_sel_hi:[1,0]
	v_pk_mul_f32 v[78:79], v[18:19], v[58:59] op_sel_hi:[1,0]
	v_pk_mul_f32 v[80:81], v[16:17], v[58:59] op_sel_hi:[1,0]
	v_pk_mul_f32 v[76:77], v[4:5], v[76:77]
	v_pk_mul_f32 v[74:75], v[6:7], v[74:75]
	v_pk_mul_f32 v[80:81], v[0:1], v[80:81]
	v_pk_mul_f32 v[78:79], v[2:3], v[78:79]
	s_waitcnt vmcnt(0)
	v_pk_fma_f32 v[38:39], v[38:39], v[74:75], v[46:47]
	v_pk_fma_f32 v[36:37], v[36:37], v[76:77], v[44:45]
	v_pk_fma_f32 v[42:43], v[34:35], v[78:79], v[42:43]
	v_pk_fma_f32 v[34:35], v[32:33], v[80:81], v[40:41]
	v_cvt_pk_bf16_f32 v32, v36, v37
	v_cvt_pk_bf16_f32 v33, v38, v39
	v_cvt_pk_bf16_f32 v34, v34, v35
	v_cvt_pk_bf16_f32 v35, v42, v43
	global_store_dwordx4 v[72:73], v[32:35], off
	global_load_dwordx4 v[32:35], v[68:69], off
	s_nop 0
	global_load_dwordx4 v[36:39], v[68:69], off offset:16
	global_load_dwordx4 v[40:43], v[70:71], off offset:2048
	global_load_dwordx4 v[44:47], v[70:71], off offset:2064
	v_pk_mul_f32 v[68:69], v[30:31], v[58:59] op_sel_hi:[1,0]
	v_pk_mul_f32 v[70:71], v[28:29], v[58:59] op_sel_hi:[1,0]
	v_pk_mul_f32 v[74:75], v[26:27], v[58:59] op_sel_hi:[1,0]
	v_pk_mul_f32 v[58:59], v[24:25], v[58:59] op_sel_hi:[1,0]
	v_pk_mul_f32 v[70:71], v[12:13], v[70:71]
	v_pk_mul_f32 v[68:69], v[14:15], v[68:69]
	v_pk_mul_f32 v[58:59], v[8:9], v[58:59]
	v_pk_mul_f32 v[74:75], v[10:11], v[74:75]
	s_waitcnt vmcnt(3)
	v_pk_add_f32 v[34:35], v[34:35], 1.0 op_sel_hi:[1,0]
	v_pk_add_f32 v[32:33], v[32:33], 1.0 op_sel_hi:[1,0]
	s_waitcnt vmcnt(2)
	v_pk_add_f32 v[38:39], v[38:39], 1.0 op_sel_hi:[1,0]
	v_pk_add_f32 v[36:37], v[36:37], 1.0 op_sel_hi:[1,0]
	s_waitcnt vmcnt(1)
	v_pk_fma_f32 v[34:35], v[34:35], v[68:69], v[42:43]
	v_pk_fma_f32 v[32:33], v[32:33], v[70:71], v[40:41]
	s_waitcnt vmcnt(0)
	v_pk_fma_f32 v[38:39], v[74:75], v[38:39], v[46:47]
	v_pk_fma_f32 v[36:37], v[58:59], v[36:37], v[44:45]
	v_cvt_pk_bf16_f32 v32, v32, v33
	v_cvt_pk_bf16_f32 v33, v34, v35
	v_cvt_pk_bf16_f32 v34, v36, v37
	v_cvt_pk_bf16_f32 v35, v38, v39
	global_store_dwordx4 v[72:73], v[32:35], off offset:1024
	s_branch .Lp1_mid
; __device__ __forceinline__ u32x4 pk8(f32x4 a, f32x4 b) { u32x4 w; w.x = pk2(a[0], a[1]); w.y = pk2(a[2], a[3]); w.z = pk2(b[0], b[1]); w.w = pk2(b[2], b[3]); return w; }
; __device__ __forceinline__ float sumsq4(f32x4 x) { return (x[0] * x[0] + x[1] * x[1]) + (x[2] * x[2] + x[3] * x[3]); }
; __device__ __forceinline__ void phase1(const Ptrs& P, int G) {
;     ...
;         for (int r = 0; r < 2; ++r) { const int row = row0 + r * NGW; if (row < T) {
;             float s = 0.f;
; #pragma unroll
;             for (int j = 0; j < 2; ++j) s += sumsq4(v[r][j][0]) + sumsq4(v[r][j][1]);
;             const int b = row >> 11;
;             const float rstd = __builtin_amdgcn_rsqf(wave_sum(s) * (1.0f / DM) + EPS);
; #pragma unroll
;             for (int j = 0; j < 2; ++j) {
;                 const int col = 512 * j + 8 * lane;
;                 const f32x4 sha = *(const f32x4*)(mod + b * 3072 + col), shb = *(const f32x4*)(mod + b * 3072 + col + 4);
;                 const f32x4 sca = *(const f32x4*)(mod + b * 3072 + 1024 + col), scb = *(const f32x4*)(mod + b * 3072 + 1024 + col + 4);
;                 const f32x4 ha = v[r][j][0] * rstd * g[j][0] * (sca + 1.0f) + sha, hb = v[r][j][1] * rstd * g[j][1] * (scb + 1.0f) + shb;
;                 *(u32x4*)(H + (size_t)row * DM + col) = pk8(ha, hb);
;             } } }
.Lp1_mid:
	s_or_b64 exec, exec, s[10:11]
	v_mov_b32_e32 v58, v96
	v_mov_b32_e32 v59, v97
	v_mov_b32_e32 v56, v100
	v_mov_b32_e32 v57, v101
	v_cmp_gt_i32_e32 vcc, s12, v56
	v_ashrrev_i32_e32 v55, 11, v58
	v_mul_i32_i24_e32 v68, 0xc00, v55
	v_ashrrev_i32_e32 v69, 31, v68
	v_lshl_add_u64 v[76:77], v[68:69], 2, s[4:5]
	v_lshl_add_u64 v[86:87], v[76:77], 0, s[8:9]
	v_lshl_add_u64 v[78:79], v[86:87], 0, v[48:49]
	global_load_dwordx4 v[68:71], v[78:79], off offset:16
	global_load_dwordx4 v[72:75], v[78:79], off
	v_lshl_add_u64 v[88:89], v[76:77], 0, v[48:49]
	global_load_dwordx4 v[76:79], v[88:89], off offset:16
	global_load_dwordx4 v[80:83], v[88:89], off
	s_waitcnt vmcnt(6)
	v_mov_b32_e32 v90, v157
	s_waitcnt vmcnt(4)
	v_mov_b32_e32 v91, v149
	v_mov_b32_e32 v84, v156
	v_mov_b32_e32 v85, v148
	v_pk_mul_f32 v[90:91], v[90:91], v[90:91]
	v_mov_b32_e32 v92, v159
	v_mov_b32_e32 v93, v151
	v_pk_fma_f32 v[84:85], v[84:85], v[84:85], v[90:91]
	v_mov_b32_e32 v90, v158
	v_mov_b32_e32 v91, v150
	v_pk_mul_f32 v[92:93], v[92:93], v[92:93]
	v_mov_b32_e32 v94, v155
	v_pk_fma_f32 v[90:91], v[90:91], v[90:91], v[92:93]
	v_mov_b32_e32 v92, v153
	v_mov_b32_e32 v93, v145
	v_pk_add_f32 v[84:85], v[84:85], v[90:91]
	v_mov_b32_e32 v90, v152
	v_mov_b32_e32 v91, v144
	v_pk_mul_f32 v[92:93], v[92:93], v[92:93]
	v_mov_b32_e32 v95, v147
	v_pk_fma_f32 v[90:91], v[90:91], v[90:91], v[92:93]
	v_mov_b32_e32 v92, v154
	v_mov_b32_e32 v93, v146
	v_pk_mul_f32 v[94:95], v[94:95], v[94:95]
	v_lshlrev_b64 v[58:59], 11, v[58:59]
	v_pk_fma_f32 v[92:93], v[92:93], v[92:93], v[94:95]
	v_lshl_add_u64 v[58:59], v[52:53], 0, v[58:59]
	v_pk_add_f32 v[90:91], v[90:91], v[92:93]
	s_waitcnt vmcnt(3)
	v_pk_add_f32 v[70:71], v[70:71], 1.0 op_sel_hi:[1,0]
	v_pk_add_f32 v[84:85], v[84:85], v[90:91]
	s_waitcnt vmcnt(2)
	v_pk_add_f32 v[74:75], v[74:75], 1.0 op_sel_hi:[1,0]
	v_add_f32_e32 v55, v84, v85
	ds_bpermute_b32 v67, v60, v55
	v_pk_add_f32 v[72:73], v[72:73], 1.0 op_sel_hi:[1,0]
	v_pk_add_f32 v[68:69], v[68:69], 1.0 op_sel_hi:[1,0]
	s_waitcnt lgkmcnt(0)
	v_add_f32_e32 v55, v55, v67
	ds_bpermute_b32 v67, v61, v55
	s_waitcnt lgkmcnt(0)
	v_add_f32_e32 v55, v55, v67
	ds_bpermute_b32 v67, v62, v55
	s_waitcnt lgkmcnt(0)
	v_add_f32_e32 v55, v55, v67
	ds_bpermute_b32 v67, v63, v55
	s_waitcnt lgkmcnt(0)
	v_add_f32_e32 v55, v55, v67
	ds_bpermute_b32 v67, v64, v55
	s_waitcnt lgkmcnt(0)
	v_add_f32_e32 v55, v55, v67
	ds_bpermute_b32 v67, v65, v55
	s_waitcnt lgkmcnt(0)
	v_add_f32_e32 v55, v55, v67
	v_fmamk_f32 v55, v55, 0x3a800000, v66
	v_rsq_f32_e32 v84, v55
	v_mov_b32_e32 v55, v49
	v_lshl_add_u64 v[86:87], v[86:87], 0, v[54:55]
	v_pk_mul_f32 v[158:159], v[158:159], v[84:85] op_sel_hi:[1,0]
	v_pk_mul_f32 v[156:157], v[156:157], v[84:85] op_sel_hi:[1,0]
	v_pk_mul_f32 v[154:155], v[154:155], v[84:85] op_sel_hi:[1,0]
	v_pk_mul_f32 v[152:153], v[152:153], v[84:85] op_sel_hi:[1,0]
	v_pk_mul_f32 v[156:157], v[4:5], v[156:157]
	v_pk_mul_f32 v[158:159], v[6:7], v[158:159]
	v_pk_mul_f32 v[152:153], v[0:1], v[152:153]
	v_pk_mul_f32 v[154:155], v[2:3], v[154:155]
	s_waitcnt vmcnt(0)
	v_pk_fma_f32 v[158:159], v[74:75], v[158:159], v[82:83]
	v_pk_fma_f32 v[156:157], v[72:73], v[156:157], v[80:81]
	v_pk_fma_f32 v[70:71], v[70:71], v[154:155], v[78:79]
	v_pk_fma_f32 v[154:155], v[68:69], v[152:153], v[76:77]
	v_cvt_pk_bf16_f32 v152, v156, v157
	v_cvt_pk_bf16_f32 v153, v158, v159
	v_cvt_pk_bf16_f32 v154, v154, v155
	v_cvt_pk_bf16_f32 v155, v70, v71
	global_store_dwordx4 v[58:59], v[152:155], off
	global_load_dwordx4 v[152:155], v[86:87], off
	s_nop 0
	global_load_dwordx4 v[156:159], v[86:87], off offset:16
	global_load_dwordx4 v[68:71], v[88:89], off offset:2048
	global_load_dwordx4 v[72:75], v[88:89], off offset:2064
	v_pk_mul_f32 v[150:151], v[150:151], v[84:85] op_sel_hi:[1,0]
	v_pk_mul_f32 v[148:149], v[148:149], v[84:85] op_sel_hi:[1,0]
	v_pk_mul_f32 v[146:147], v[146:147], v[84:85] op_sel_hi:[1,0]
	v_pk_mul_f32 v[144:145], v[144:145], v[84:85] op_sel_hi:[1,0]
	v_pk_mul_f32 v[148:149], v[12:13], v[148:149]
	v_pk_mul_f32 v[150:151], v[14:15], v[150:151]
	v_pk_mul_f32 v[144:145], v[8:9], v[144:145]
	v_pk_mul_f32 v[146:147], v[10:11], v[146:147]
	s_waitcnt vmcnt(3)
	v_pk_add_f32 v[154:155], v[154:155], 1.0 op_sel_hi:[1,0]
	v_pk_add_f32 v[152:153], v[152:153], 1.0 op_sel_hi:[1,0]
	s_waitcnt vmcnt(2)
	v_pk_add_f32 v[158:159], v[158:159], 1.0 op_sel_hi:[1,0]
	v_pk_add_f32 v[156:157], v[156:157], 1.0 op_sel_hi:[1,0]
	s_waitcnt vmcnt(1)
	v_pk_fma_f32 v[150:151], v[154:155], v[150:151], v[70:71]
	v_pk_fma_f32 v[148:149], v[152:153], v[148:149], v[68:69]
	s_waitcnt vmcnt(0)
	v_pk_fma_f32 v[152:153], v[146:147], v[158:159], v[74:75]
	v_pk_fma_f32 v[146:147], v[144:145], v[156:157], v[72:73]
	v_cvt_pk_bf16_f32 v144, v148, v149
	v_cvt_pk_bf16_f32 v145, v150, v151
	v_cvt_pk_bf16_f32 v146, v146, v147
	v_cvt_pk_bf16_f32 v147, v152, v153
	global_store_dwordx4 v[58:59], v[144:147], off offset:1024
	s_and_saveexec_b64 s[10:11], vcc
	s_cbranch_execz .LBB0_279
; __device__ __forceinline__ u32x4 pk8(f32x4 a, f32x4 b) { u32x4 w; w.x = pk2(a[0], a[1]); w.y = pk2(a[2], a[3]); w.z = pk2(b[0], b[1]); w.w = pk2(b[2], b[3]); return w; }
; __device__ __forceinline__ float sumsq4(f32x4 x) { return (x[0] * x[0] + x[1] * x[1]) + (x[2] * x[2] + x[3] * x[3]); }
; __device__ __forceinline__ void phase1(const Ptrs& P, int G) {
;     ...
;         for (int r = 0; r < 2; ++r) { const int row = row0 + r * NGW; if (row < T) {
;             float s = 0.f;
; #pragma unroll
;             for (int j = 0; j < 2; ++j) s += sumsq4(v[r][j][0]) + sumsq4(v[r][j][1]);
;             const int b = row >> 11;
;             const float rstd = __builtin_amdgcn_rsqf(wave_sum(s) * (1.0f / DM) + EPS);
; #pragma unroll
;             for (int j = 0; j < 2; ++j) {
;                 const int col = 512 * j + 8 * lane;
;                 const f32x4 sha = *(const f32x4*)(mod + b * 3072 + col), shb = *(const f32x4*)(mod + b * 3072 + col + 4);
;                 const f32x4 sca = *(const f32x4*)(mod + b * 3072 + 1024 + col), scb = *(const f32x4*)(mod + b * 3072 + 1024 + col + 4);
;                 const f32x4 ha = v[r][j][0] * rstd * g[j][0] * (sca + 1.0f) + sha, hb = v[r][j][1] * rstd * g[j][1] * (scb + 1.0f) + shb;
;                 *(u32x4*)(H + (size_t)row * DM + col) = pk8(ha, hb);
;             } } }
	v_ashrrev_i32_e32 v144, 11, v56
	v_mul_i32_i24_e32 v144, 0xc00, v144
	v_ashrrev_i32_e32 v145, 31, v144
	v_lshl_add_u64 v[152:153], v[144:145], 2, s[4:5]
	v_lshl_add_u64 v[68:69], v[152:153], 0, s[8:9]
	v_lshl_add_u64 v[154:155], v[68:69], 0, v[48:49]
	global_load_dwordx4 v[144:147], v[154:155], off offset:16
	global_load_dwordx4 v[148:151], v[154:155], off
	v_lshl_add_u64 v[70:71], v[152:153], 0, v[48:49]
	global_load_dwordx4 v[152:155], v[70:71], off offset:16
	global_load_dwordx4 v[156:159], v[70:71], off
	v_mov_b32_e32 v72, v141
	v_mov_b32_e32 v73, v133
	v_mov_b32_e32 v58, v140
	v_mov_b32_e32 v59, v132
	v_pk_mul_f32 v[72:73], v[72:73], v[72:73]
	v_mov_b32_e32 v74, v143
	v_mov_b32_e32 v75, v135
	v_pk_fma_f32 v[58:59], v[58:59], v[58:59], v[72:73]
	v_mov_b32_e32 v72, v142
	v_mov_b32_e32 v73, v134
	v_pk_mul_f32 v[74:75], v[74:75], v[74:75]
	v_mov_b32_e32 v76, v139
	v_pk_fma_f32 v[72:73], v[72:73], v[72:73], v[74:75]
	v_mov_b32_e32 v74, v137
	v_mov_b32_e32 v75, v129
	v_pk_add_f32 v[58:59], v[58:59], v[72:73]
	v_mov_b32_e32 v72, v136
	v_mov_b32_e32 v73, v128
	v_pk_mul_f32 v[74:75], v[74:75], v[74:75]
	v_mov_b32_e32 v77, v131
	v_pk_fma_f32 v[72:73], v[72:73], v[72:73], v[74:75]
	v_mov_b32_e32 v74, v138
	v_mov_b32_e32 v75, v130
	v_pk_mul_f32 v[76:77], v[76:77], v[76:77]
	v_lshl_add_u64 v[68:69], v[68:69], 0, v[54:55]
	v_pk_fma_f32 v[74:75], v[74:75], v[74:75], v[76:77]
	s_waitcnt vmcnt(3)
	v_pk_add_f32 v[146:147], v[146:147], 1.0 op_sel_hi:[1,0]
	v_pk_add_f32 v[72:73], v[72:73], v[74:75]
	s_waitcnt vmcnt(2)
	v_pk_add_f32 v[150:151], v[150:151], 1.0 op_sel_hi:[1,0]
	v_pk_add_f32 v[58:59], v[72:73], v[58:59]
	v_pk_add_f32 v[148:149], v[148:149], 1.0 op_sel_hi:[1,0]
	v_add_f32_e32 v58, v58, v59
	ds_bpermute_b32 v59, v60, v58
	v_pk_add_f32 v[144:145], v[144:145], 1.0 op_sel_hi:[1,0]
	v_lshlrev_b64 v[72:73], 11, v[56:57]
	v_lshl_add_u64 v[72:73], v[52:53], 0, v[72:73]
	s_waitcnt lgkmcnt(0)
	v_add_f32_e32 v58, v58, v59
	ds_bpermute_b32 v59, v61, v58
	s_waitcnt lgkmcnt(0)
	v_add_f32_e32 v58, v58, v59
	ds_bpermute_b32 v59, v62, v58
	s_waitcnt lgkmcnt(0)
	v_add_f32_e32 v58, v58, v59
	ds_bpermute_b32 v59, v63, v58
	s_waitcnt lgkmcnt(0)
	v_add_f32_e32 v58, v58, v59
	ds_bpermute_b32 v59, v64, v58
	s_waitcnt lgkmcnt(0)
	v_add_f32_e32 v58, v58, v59
	ds_bpermute_b32 v59, v65, v58
	s_waitcnt lgkmcnt(0)
	v_add_f32_e32 v58, v58, v59
	v_fmamk_f32 v58, v58, 0x3a800000, v66
	v_rsq_f32_e32 v58, v58
	s_nop 0
	v_pk_mul_f32 v[74:75], v[134:135], v[58:59] op_sel_hi:[1,0]
	v_pk_mul_f32 v[76:77], v[132:133], v[58:59] op_sel_hi:[1,0]
	v_pk_mul_f32 v[78:79], v[130:131], v[58:59] op_sel_hi:[1,0]
	v_pk_mul_f32 v[80:81], v[128:129], v[58:59] op_sel_hi:[1,0]
	v_pk_mul_f32 v[76:77], v[4:5], v[76:77]
	v_pk_mul_f32 v[74:75], v[6:7], v[74:75]
	v_pk_mul_f32 v[80:81], v[0:1], v[80:81]
	v_pk_mul_f32 v[78:79], v[2:3], v[78:79]
	s_waitcnt vmcnt(0)
	v_pk_fma_f32 v[150:151], v[150:151], v[74:75], v[158:159]
	v_pk_fma_f32 v[148:149], v[148:149], v[76:77], v[156:157]
	v_pk_fma_f32 v[154:155], v[146:147], v[78:79], v[154:155]
	v_pk_fma_f32 v[146:147], v[144:145], v[80:81], v[152:153]
	v_cvt_pk_bf16_f32 v144, v148, v149
	v_cvt_pk_bf16_f32 v145, v150, v151
	v_cvt_pk_bf16_f32 v146, v146, v147
	v_cvt_pk_bf16_f32 v147, v154, v155
	global_store_dwordx4 v[72:73], v[144:147], off
	global_load_dwordx4 v[144:147], v[68:69], off
	s_nop 0
	global_load_dwordx4 v[148:151], v[68:69], off offset:16
	global_load_dwordx4 v[152:155], v[70:71], off offset:2048
	global_load_dwordx4 v[156:159], v[70:71], off offset:2064
	v_pk_mul_f32 v[68:69], v[142:143], v[58:59] op_sel_hi:[1,0]
	v_pk_mul_f32 v[70:71], v[140:141], v[58:59] op_sel_hi:[1,0]
	v_pk_mul_f32 v[74:75], v[138:139], v[58:59] op_sel_hi:[1,0]
	v_pk_mul_f32 v[58:59], v[136:137], v[58:59] op_sel_hi:[1,0]
	v_pk_mul_f32 v[70:71], v[12:13], v[70:71]
	v_pk_mul_f32 v[68:69], v[14:15], v[68:69]
	v_pk_mul_f32 v[58:59], v[8:9], v[58:59]
	v_pk_mul_f32 v[74:75], v[10:11], v[74:75]
	s_waitcnt vmcnt(3)
	v_pk_add_f32 v[146:147], v[146:147], 1.0 op_sel_hi:[1,0]
	v_pk_add_f32 v[144:145], v[144:145], 1.0 op_sel_hi:[1,0]
	s_waitcnt vmcnt(2)
	v_pk_add_f32 v[150:151], v[150:151], 1.0 op_sel_hi:[1,0]
	v_pk_add_f32 v[148:149], v[148:149], 1.0 op_sel_hi:[1,0]
	s_waitcnt vmcnt(1)
	v_pk_fma_f32 v[146:147], v[146:147], v[68:69], v[154:155]
	v_pk_fma_f32 v[144:145], v[144:145], v[70:71], v[152:153]
	s_waitcnt vmcnt(0)
	v_pk_fma_f32 v[150:151], v[74:75], v[150:151], v[158:159]
	v_pk_fma_f32 v[148:149], v[58:59], v[148:149], v[156:157]
	v_cvt_pk_bf16_f32 v144, v144, v145
	v_cvt_pk_bf16_f32 v145, v146, v147
	v_cvt_pk_bf16_f32 v146, v148, v149
	v_cvt_pk_bf16_f32 v147, v150, v151
	global_store_dwordx4 v[72:73], v[144:147], off offset:1024
	s_branch .LBB0_279
